# UP3 MT=3 f16 store epilogue via LDS tile transpose, 16B row-major stores
# baseline (speedup 1.0000x reference)
; DI int otid() { int t = threadIdx.x; asm volatile("" : "+v"(t)); return t; }
; DI bf16_t cv1(float x) { return (bf16_t)(pk2(x, 0.f) & 0xffffu); }
; DI int crow(int i, int h) { return (i & 3) + 8 * (i >> 2) + 4 * h; }
; template <int MT> DI void st_bf16(bf16_t* base, int ld, int d2, int col0, const f32x16 (&acc)[MT][NT]) {
;     const int lane = otid() & 63, r = lane & 31, h = lane >> 5;
; #pragma unroll
;     for (int mi = 0; mi < MT; ++mi)
; #pragma unroll
;         for (int nj = 0; nj < NT; ++nj)
; #pragma unroll
;             for (int i = 0; i < 16; ++i) base[(mi * 32 + crow(i, h) + (mi == 2 ? d2 : 0)) * ld + col0 + nj * 32 + r] = cv1(acc[mi][nj][i]);
; }
.LBB0_469:
	s_and_saveexec_b64 s[56:57], s[4:5]
	s_cbranch_execz .LBB0_458
	s_waitcnt vmcnt(0)
	v_mul_u32_u24_e32 v120, 0xa00, v223
	v_add_u32_e32 v120, 0xcc00, v120
	v_and_b32_e32 v112, 31, v176
	v_lshl_add_u32 v112, v112, 1, v120
	v_lshrrev_b32_e32 v113, 5, v176
	v_and_b32_e32 v113, 1, v113
	v_mul_u32_u24_e32 v113, 320, v113
	v_add_u32_e32 v112, v112, v113
	v_and_b32_e32 v113, 63, v176
	v_lshrrev_b32_e32 v114, 2, v113
	v_and_b32_e32 v113, 3, v113
	v_lshlrev_b32_e32 v113, 4, v113
	v_mul_u32_u24_e32 v121, 80, v114
	v_add_u32_e32 v120, v120, v121
	v_mul_u32_u24_e32 v114, 0x2c00, v114
	v_add_u32_e32 v114, v114, v113
	v_add_u32_e32 v113, v120, v113
	v_lshl_add_u32 v114, v233, 7, v114
	v_cvt_f16_f32_e32 v121, v96
	ds_write_b16 v112, v121
	v_cvt_f16_f32_e32 v122, v97
	ds_write_b16 v112, v122 offset:80
	v_cvt_f16_f32_e32 v123, v98
	ds_write_b16 v112, v123 offset:160
	v_cvt_f16_f32_e32 v124, v99
	ds_write_b16 v112, v124 offset:240
	v_cvt_f16_f32_e32 v125, v100
	ds_write_b16 v112, v125 offset:640
	v_cvt_f16_f32_e32 v126, v101
	ds_write_b16 v112, v126 offset:720
	v_cvt_f16_f32_e32 v121, v102
	ds_write_b16 v112, v121 offset:800
	v_cvt_f16_f32_e32 v122, v103
	ds_write_b16 v112, v122 offset:880
	v_cvt_f16_f32_e32 v123, v104
	ds_write_b16 v112, v123 offset:1280
	v_cvt_f16_f32_e32 v124, v105
	ds_write_b16 v112, v124 offset:1360
	v_cvt_f16_f32_e32 v125, v106
	ds_write_b16 v112, v125 offset:1440
	v_cvt_f16_f32_e32 v126, v107
	ds_write_b16 v112, v126 offset:1520
	v_cvt_f16_f32_e32 v121, v108
	ds_write_b16 v112, v121 offset:1920
	v_cvt_f16_f32_e32 v122, v109
	ds_write_b16 v112, v122 offset:2000
	v_cvt_f16_f32_e32 v123, v110
	ds_write_b16 v112, v123 offset:2080
	v_cvt_f16_f32_e32 v124, v111
	ds_write_b16 v112, v124 offset:2160
	s_waitcnt lgkmcnt(0)
	ds_read_b128 v[2:5], v113
	ds_read_b128 v[116:119], v113 offset:1280
	s_waitcnt lgkmcnt(0)
	v_add_u32_e32 v125, 0, v114
	global_store_dwordx4 v125, v[2:5], s[6:7]
	v_add_u32_e32 v126, 0x2c000, v114
	global_store_dwordx4 v126, v[116:119], s[6:7]
	s_nop 1
	v_cvt_f16_f32_e32 v121, v80
	ds_write_b16 v112, v121
	v_cvt_f16_f32_e32 v122, v81
	ds_write_b16 v112, v122 offset:80
	v_cvt_f16_f32_e32 v123, v82
	ds_write_b16 v112, v123 offset:160
	v_cvt_f16_f32_e32 v124, v83
	ds_write_b16 v112, v124 offset:240
	v_cvt_f16_f32_e32 v125, v84
	ds_write_b16 v112, v125 offset:640
	v_cvt_f16_f32_e32 v126, v85
	ds_write_b16 v112, v126 offset:720
	v_cvt_f16_f32_e32 v121, v86
	ds_write_b16 v112, v121 offset:800
	v_cvt_f16_f32_e32 v122, v87
	ds_write_b16 v112, v122 offset:880
	v_cvt_f16_f32_e32 v123, v88
	ds_write_b16 v112, v123 offset:1280
	v_cvt_f16_f32_e32 v124, v89
	ds_write_b16 v112, v124 offset:1360
	v_cvt_f16_f32_e32 v125, v90
	ds_write_b16 v112, v125 offset:1440
	v_cvt_f16_f32_e32 v126, v91
	ds_write_b16 v112, v126 offset:1520
	v_cvt_f16_f32_e32 v121, v92
	ds_write_b16 v112, v121 offset:1920
	v_cvt_f16_f32_e32 v122, v93
	ds_write_b16 v112, v122 offset:2000
	v_cvt_f16_f32_e32 v123, v94
	ds_write_b16 v112, v123 offset:2080
	v_cvt_f16_f32_e32 v124, v95
	ds_write_b16 v112, v124 offset:2160
	s_waitcnt lgkmcnt(0)
	ds_read_b128 v[2:5], v113
	ds_read_b128 v[116:119], v113 offset:1280
	s_waitcnt lgkmcnt(0)
	v_add_u32_e32 v125, 64, v114
	global_store_dwordx4 v125, v[2:5], s[6:7]
	v_add_u32_e32 v126, 0x2c040, v114
	global_store_dwordx4 v126, v[116:119], s[6:7]
	s_nop 1
	v_cvt_f16_f32_e32 v121, v64
	ds_write_b16 v112, v121
	v_cvt_f16_f32_e32 v122, v65
	ds_write_b16 v112, v122 offset:80
	v_cvt_f16_f32_e32 v123, v66
	ds_write_b16 v112, v123 offset:160
	v_cvt_f16_f32_e32 v124, v67
	ds_write_b16 v112, v124 offset:240
	v_cvt_f16_f32_e32 v125, v68
	ds_write_b16 v112, v125 offset:640
	v_cvt_f16_f32_e32 v126, v69
	ds_write_b16 v112, v126 offset:720
	v_cvt_f16_f32_e32 v121, v70
	ds_write_b16 v112, v121 offset:800
	v_cvt_f16_f32_e32 v122, v71
	ds_write_b16 v112, v122 offset:880
	v_cvt_f16_f32_e32 v123, v72
	ds_write_b16 v112, v123 offset:1280
	v_cvt_f16_f32_e32 v124, v73
	ds_write_b16 v112, v124 offset:1360
	v_cvt_f16_f32_e32 v125, v74
	ds_write_b16 v112, v125 offset:1440
	v_cvt_f16_f32_e32 v126, v75
	ds_write_b16 v112, v126 offset:1520
	v_cvt_f16_f32_e32 v121, v76
	ds_write_b16 v112, v121 offset:1920
	v_cvt_f16_f32_e32 v122, v77
	ds_write_b16 v112, v122 offset:2000
	v_cvt_f16_f32_e32 v123, v78
	ds_write_b16 v112, v123 offset:2080
	v_cvt_f16_f32_e32 v124, v79
	ds_write_b16 v112, v124 offset:2160
	s_waitcnt lgkmcnt(0)
	ds_read_b128 v[2:5], v113
	ds_read_b128 v[116:119], v113 offset:1280
	s_waitcnt lgkmcnt(0)
; DI int otid() { int t = threadIdx.x; asm volatile("" : "+v"(t)); return t; }
; DI bf16_t cv1(float x) { return (bf16_t)(pk2(x, 0.f) & 0xffffu); }
; DI int crow(int i, int h) { return (i & 3) + 8 * (i >> 2) + 4 * h; }
; template <int MT> DI void st_bf16(bf16_t* base, int ld, int d2, int col0, const f32x16 (&acc)[MT][NT]) {
;     const int lane = otid() & 63, r = lane & 31, h = lane >> 5;
; #pragma unroll
;     for (int mi = 0; mi < MT; ++mi)
; #pragma unroll
;         for (int nj = 0; nj < NT; ++nj)
; #pragma unroll
;             for (int i = 0; i < 16; ++i) base[(mi * 32 + crow(i, h) + (mi == 2 ? d2 : 0)) * ld + col0 + nj * 32 + r] = cv1(acc[mi][nj][i]);
; }
;     DI void operator()(int unit, const f32x16 (&acc)[MT][NT]) const {
;     ...
;                     const int lr = mi * 32 + crow(i, h), c = unit * UW + nj * 32 + r;
;                     if (mi == 1) { if (lr >= 62) { halo[(lr - 62) * DFF2 + c] = acc[mi][nj][i]; if (pconv) pconv[(lr - 62) * DFF2 + c] = acc[mi][nj][i]; } }
	v_add_u32_e32 v125, 0x58000, v114
	global_store_dwordx4 v125, v[2:5], s[6:7]
	v_add_u32_e32 v126, 0x84000, v114
	global_store_dwordx4 v126, v[116:119], s[6:7]
	s_nop 1
	v_cvt_f16_f32_e32 v121, v48
	ds_write_b16 v112, v121
	v_cvt_f16_f32_e32 v122, v49
	ds_write_b16 v112, v122 offset:80
	v_cvt_f16_f32_e32 v123, v50
	ds_write_b16 v112, v123 offset:160
	v_cvt_f16_f32_e32 v124, v51
	ds_write_b16 v112, v124 offset:240
	v_cvt_f16_f32_e32 v125, v52
	ds_write_b16 v112, v125 offset:640
	v_cvt_f16_f32_e32 v126, v53
	ds_write_b16 v112, v126 offset:720
	v_cvt_f16_f32_e32 v121, v54
	ds_write_b16 v112, v121 offset:800
	v_cvt_f16_f32_e32 v122, v55
	ds_write_b16 v112, v122 offset:880
	v_cvt_f16_f32_e32 v123, v56
	ds_write_b16 v112, v123 offset:1280
	v_cvt_f16_f32_e32 v124, v57
	ds_write_b16 v112, v124 offset:1360
	v_cvt_f16_f32_e32 v125, v58
	ds_write_b16 v112, v125 offset:1440
	v_cvt_f16_f32_e32 v126, v59
	ds_write_b16 v112, v126 offset:1520
	v_cvt_f16_f32_e32 v121, v60
	ds_write_b16 v112, v121 offset:1920
	v_cvt_f16_f32_e32 v122, v61
	ds_write_b16 v112, v122 offset:2000
	v_cvt_f16_f32_e32 v123, v62
	ds_write_b16 v112, v123 offset:2080
	v_cvt_f16_f32_e32 v124, v63
	ds_write_b16 v112, v124 offset:2160
	s_waitcnt lgkmcnt(0)
	ds_read_b128 v[2:5], v113
	ds_read_b128 v[116:119], v113 offset:1280
	s_waitcnt lgkmcnt(0)
	v_add_u32_e32 v125, 0x58040, v114
	global_store_dwordx4 v125, v[2:5], s[6:7]
	v_add_u32_e32 v126, 0x84040, v114
	global_store_dwordx4 v126, v[116:119], s[6:7]
	s_nop 1
	s_mul_i32 s101, s59, 0x2c00
	v_add_u32_e32 v120, s101, v114
	v_cvt_f16_f32_e32 v121, v32
	ds_write_b16 v112, v121
	v_cvt_f16_f32_e32 v122, v33
	ds_write_b16 v112, v122 offset:80
	v_cvt_f16_f32_e32 v123, v34
	ds_write_b16 v112, v123 offset:160
	v_cvt_f16_f32_e32 v124, v35
	ds_write_b16 v112, v124 offset:240
	v_cvt_f16_f32_e32 v125, v36
	ds_write_b16 v112, v125 offset:640
	v_cvt_f16_f32_e32 v126, v37
	ds_write_b16 v112, v126 offset:720
	v_cvt_f16_f32_e32 v121, v38
	ds_write_b16 v112, v121 offset:800
	v_cvt_f16_f32_e32 v122, v39
	ds_write_b16 v112, v122 offset:880
	v_cvt_f16_f32_e32 v123, v40
	ds_write_b16 v112, v123 offset:1280
	v_cvt_f16_f32_e32 v124, v41
	ds_write_b16 v112, v124 offset:1360
	v_cvt_f16_f32_e32 v125, v42
	ds_write_b16 v112, v125 offset:1440
	v_cvt_f16_f32_e32 v126, v43
	ds_write_b16 v112, v126 offset:1520
	v_cvt_f16_f32_e32 v121, v44
	ds_write_b16 v112, v121 offset:1920
	v_cvt_f16_f32_e32 v122, v45
	ds_write_b16 v112, v122 offset:2000
	v_cvt_f16_f32_e32 v123, v46
	ds_write_b16 v112, v123 offset:2080
	v_cvt_f16_f32_e32 v124, v47
	ds_write_b16 v112, v124 offset:2160
	s_waitcnt lgkmcnt(0)
	ds_read_b128 v[2:5], v113
	ds_read_b128 v[116:119], v113 offset:1280
	s_waitcnt lgkmcnt(0)
	v_add_u32_e32 v125, 0, v120
	global_store_dwordx4 v125, v[2:5], s[6:7]
	v_add_u32_e32 v126, 0x2c000, v120
	global_store_dwordx4 v126, v[116:119], s[6:7]
	s_nop 1
	v_cvt_f16_f32_e32 v121, v16
	ds_write_b16 v112, v121
	v_cvt_f16_f32_e32 v122, v17
	ds_write_b16 v112, v122 offset:80
	v_cvt_f16_f32_e32 v123, v18
	ds_write_b16 v112, v123 offset:160
	v_cvt_f16_f32_e32 v124, v19
	ds_write_b16 v112, v124 offset:240
	v_cvt_f16_f32_e32 v125, v20
	ds_write_b16 v112, v125 offset:640
	v_cvt_f16_f32_e32 v126, v21
	ds_write_b16 v112, v126 offset:720
	v_cvt_f16_f32_e32 v121, v22
	ds_write_b16 v112, v121 offset:800
	v_cvt_f16_f32_e32 v122, v23
	ds_write_b16 v112, v122 offset:880
	v_cvt_f16_f32_e32 v123, v24
	ds_write_b16 v112, v123 offset:1280
	v_cvt_f16_f32_e32 v124, v25
	ds_write_b16 v112, v124 offset:1360
	v_cvt_f16_f32_e32 v125, v26
	ds_write_b16 v112, v125 offset:1440
	v_cvt_f16_f32_e32 v126, v27
	ds_write_b16 v112, v126 offset:1520
	v_cvt_f16_f32_e32 v121, v28
	ds_write_b16 v112, v121 offset:1920
	v_cvt_f16_f32_e32 v122, v29
	ds_write_b16 v112, v122 offset:2000
	v_cvt_f16_f32_e32 v123, v30
	ds_write_b16 v112, v123 offset:2080
	v_cvt_f16_f32_e32 v124, v31
	ds_write_b16 v112, v124 offset:2160
	s_waitcnt lgkmcnt(0)
	ds_read_b128 v[2:5], v113
	ds_read_b128 v[116:119], v113 offset:1280
	s_waitcnt lgkmcnt(0)
	v_add_u32_e32 v125, 64, v120
	global_store_dwordx4 v125, v[2:5], s[6:7]
	v_add_u32_e32 v126, 0x2c040, v120
	global_store_dwordx4 v126, v[116:119], s[6:7]
	s_nop 1
	v_lshlrev_b32_e32 v0, 6, v233
	v_mov_b32_e32 v3, v176
	s_nop 0
	v_lshrrev_b32_e32 v2, 3, v3
	v_and_b32_e32 v4, 4, v2
	v_and_or_b32 v2, v3, 31, v0
	v_and_b32_e32 v3, 32, v3
	v_add_u32_e32 v5, 0xfffaac00, v2
	v_or_b32_e32 v0, 58, v4
	v_cmp_ne_u32_e32 vcc, 0, v3
	s_and_saveexec_b64 s[0:1], vcc
	s_cbranch_execz .LBB0_472
	v_mad_u32_u24 v6, v0, s44, v5
	v_ashrrev_i32_e32 v7, 31, v6
	v_lshl_add_u64 v[6:7], v[6:7], 2, s[8:9]
	global_store_dword v[6:7], v78, off
